# hand-written global barrier (monotonic counters, last leader releases all XCCs directly) on seams G1->pre, pre->scan, scan->gate, gate->G2
# baseline (speedup 1.0000x reference)
.LBB0_2:
	s_load_dword s26, s[0:1], 0xc0
	v_readfirstlane_b32 s3, v194
	s_cmp_gt_u32 s3, 63
	s_cbranch_scc1 .LBB0_6
	v_mbcnt_lo_u32_b32 v1, -1, 0
	v_mbcnt_hi_u32_b32 v1, -1, v1
	s_nop 0
	v_cmp_eq_u32_e32 vcc, 0, v1
	s_and_saveexec_b64 s[6:7], vcc
	s_cbranch_execz .LBB0_5
	s_add_i32 s3, 0, 0x23ff0
	v_mov_b32_e32 v1, 0
	v_mov_b32_e32 v2, s3
	s_add_i32 s3, 0, 0x23ff4
	ds_write_b32 v2, v1
	v_mov_b32_e32 v2, s3
	ds_write_b32 v2, v1
	v_mov_b32_e32 v2, 0x23800
	ds_write_b32 v2, v1

.LBB0_164:
	s_waitcnt vmcnt(0)
	v_readfirstlane_b32 s0, v194
	s_cmp_gt_u32 s0, 63
	s_waitcnt vmcnt(0)
	s_barrier
	s_cbranch_scc1 .LBB0_218
	v_mbcnt_lo_u32_b32 v0, -1, 0
	v_mbcnt_hi_u32_b32 v0, -1, v0
	s_nop 0
	v_cmp_eq_u32_e32 vcc, 0, v0
	s_and_saveexec_b64 s[0:1], vcc
	s_cbranch_execz .LBB0_217
	v_mov_b32_e32 v0, 0x23ff0
	s_waitcnt vmcnt(0) lgkmcnt(0)
	ds_read_b64 v[0:1], v0
	v_mov_b32_e32 v2, 0x23800
	ds_read_b32 v3, v2
	s_getreg_b32 s3, hwreg(HW_REG_XCC_ID, 0, 4)
	s_and_b32 s3, s3, 7
	s_lshl_b32 s3, s3, 8
	s_add_u32 s4, s92, 0x510000
	s_addc_u32 s5, s93, 0
	s_add_u32 s8, s3, 0x36c0
	v_mov_b32_e32 v6, s8
	v_mov_b32_e32 v7, 1
	global_atomic_add v8, v6, v7, s[4:5] sc0
	s_add_u32 s3, s3, 0x3640
	v_mov_b32_e32 v9, s3
	s_waitcnt lgkmcnt(0)
	v_add_u32_e32 v3, 1, v3
	ds_write_b32 v2, v3
	v_mul_lo_u32 v4, v3, v0
	v_mul_lo_u32 v5, v3, v1
	s_waitcnt vmcnt(0)
	v_add_u32_e32 v8, 1, v8
	v_cmp_eq_u32_e32 vcc, v8, v4
	s_cbranch_vccz .Lgb_wait_0
	buffer_wbl2 sc1
	s_waitcnt vmcnt(0)
	v_mov_b32_e32 v10, 0x3e00
	global_atomic_add v11, v10, v7, s[4:5] sc0
	s_waitcnt vmcnt(0)
	v_add_u32_e32 v11, 1, v11
	v_cmp_eq_u32_e32 vcc, v11, v5
	s_cbranch_vccz .Lgb_wait_0
	v_mov_b32_e32 v10, 0x3640
	v_mov_b32_e32 v11, 0x3740
	v_mov_b32_e32 v12, 0x3840
	v_mov_b32_e32 v13, 0x3940
	v_mov_b32_e32 v14, 0x3a40
	v_mov_b32_e32 v15, 0x3b40
	v_mov_b32_e32 v16, 0x3c40
	v_mov_b32_e32 v17, 0x3d40
	global_atomic_add v10, v7, s[4:5]
	global_atomic_add v11, v7, s[4:5]
	global_atomic_add v12, v7, s[4:5]
	global_atomic_add v13, v7, s[4:5]
	global_atomic_add v14, v7, s[4:5]
	global_atomic_add v15, v7, s[4:5]
	global_atomic_add v16, v7, s[4:5]
	global_atomic_add v17, v7, s[4:5]
.Lgb_wait_0:
	s_mov_b32 s8, 0
.Lgb_spin_0:
	global_load_dword v8, v9, s[4:5] sc1
	s_waitcnt vmcnt(0)
	v_cmp_ge_u32_e32 vcc, v8, v3
	s_cbranch_vccnz .Lgb_done_0
	s_sleep 1
	s_add_u32 s8, s8, 1
	s_cmp_lt_u32 s8, 0x40000
	s_cbranch_scc1 .Lgb_spin_0
.Lgb_done_0:
	buffer_inv sc1
	s_waitcnt vmcnt(0) lgkmcnt(0)
	s_branch .LBB0_217
	s_add_i32 s3, 0, 0x23ff0
	v_mov_b32_e32 v0, s3
	s_waitcnt vmcnt(0) expcnt(0) lgkmcnt(0)
	ds_read_b32 v2, v0
	s_add_i32 s3, 0, 0x23ff4
	v_mov_b32_e32 v0, s3
	ds_read_b32 v0, v0
	s_waitcnt lgkmcnt(1)
	v_cmp_ne_u32_e32 vcc, 0, v2
	s_cbranch_vccnz .LBB0_181
	s_mov_b32 s3, 1
	v_mov_b32_e32 v16, 0
	s_branch .LBB0_169

.LBB0_308:
	s_waitcnt vmcnt(0)
	v_readfirstlane_b32 s4, v194
	s_cmp_gt_u32 s4, 63
	v_readlane_b32 s77, v242, 9
	v_readlane_b32 s78, v241, 13
	v_readlane_b32 s40, v241, 12
	v_readlane_b32 s41, v241, 4
	s_barrier
	s_cbranch_scc1 .LBB0_362
	v_mbcnt_lo_u32_b32 v0, -1, 0
	v_mbcnt_hi_u32_b32 v0, -1, v0
	s_nop 0
	v_cmp_eq_u32_e32 vcc, 0, v0
	s_and_saveexec_b64 s[6:7], vcc
	s_cbranch_execz .LBB0_361
	v_mov_b32_e32 v0, 0x23ff0
	s_waitcnt vmcnt(0) lgkmcnt(0)
	ds_read_b64 v[0:1], v0
	v_mov_b32_e32 v2, 0x23800
	ds_read_b32 v3, v2
	s_getreg_b32 s8, hwreg(HW_REG_XCC_ID, 0, 4)
	s_and_b32 s8, s8, 7
	s_lshl_b32 s8, s8, 8
	s_add_u32 s4, s92, 0x510000
	s_addc_u32 s5, s93, 0
	s_add_u32 s9, s8, 0x36c0
	v_mov_b32_e32 v6, s9
	v_mov_b32_e32 v7, 1
	global_atomic_add v8, v6, v7, s[4:5] sc0
	s_add_u32 s8, s8, 0x3640
	v_mov_b32_e32 v9, s8
	s_waitcnt lgkmcnt(0)
	v_add_u32_e32 v3, 1, v3
	ds_write_b32 v2, v3
	v_mul_lo_u32 v4, v3, v0
	v_mul_lo_u32 v5, v3, v1
	s_waitcnt vmcnt(0)
	v_add_u32_e32 v8, 1, v8
	v_cmp_eq_u32_e32 vcc, v8, v4
	s_cbranch_vccz .Lgb_wait_1
	buffer_wbl2 sc1
	s_waitcnt vmcnt(0)
	v_mov_b32_e32 v10, 0x3e00
	global_atomic_add v11, v10, v7, s[4:5] sc0
	s_waitcnt vmcnt(0)
	v_add_u32_e32 v11, 1, v11
	v_cmp_eq_u32_e32 vcc, v11, v5
	s_cbranch_vccz .Lgb_wait_1
	v_mov_b32_e32 v10, 0x3640
	v_mov_b32_e32 v11, 0x3740
	v_mov_b32_e32 v12, 0x3840
	v_mov_b32_e32 v13, 0x3940
	v_mov_b32_e32 v14, 0x3a40
	v_mov_b32_e32 v15, 0x3b40
	v_mov_b32_e32 v16, 0x3c40
	v_mov_b32_e32 v17, 0x3d40
	global_atomic_add v10, v7, s[4:5]
	global_atomic_add v11, v7, s[4:5]
	global_atomic_add v12, v7, s[4:5]
	global_atomic_add v13, v7, s[4:5]
	global_atomic_add v14, v7, s[4:5]
	global_atomic_add v15, v7, s[4:5]
	global_atomic_add v16, v7, s[4:5]
	global_atomic_add v17, v7, s[4:5]
.Lgb_wait_1:
	s_mov_b32 s9, 0
.Lgb_spin_1:
	global_load_dword v8, v9, s[4:5] sc1
	s_waitcnt vmcnt(0)
	v_cmp_ge_u32_e32 vcc, v8, v3
	s_cbranch_vccnz .Lgb_done_1
	s_sleep 1
	s_add_u32 s9, s9, 1
	s_cmp_lt_u32 s9, 0x40000
	s_cbranch_scc1 .Lgb_spin_1
.Lgb_done_1:
	buffer_inv sc1
	s_waitcnt vmcnt(0) lgkmcnt(0)
	s_branch .LBB0_361
	s_add_i32 s4, 0, 0x23ff0
	v_mov_b32_e32 v0, s4
	s_waitcnt vmcnt(0) expcnt(0) lgkmcnt(0)
	ds_read_b32 v2, v0
	s_add_i32 s4, 0, 0x23ff4
	v_mov_b32_e32 v0, s4
	ds_read_b32 v0, v0
	s_waitcnt lgkmcnt(1)
	v_cmp_ne_u32_e32 vcc, 0, v2
	s_cbranch_vccnz .LBB0_325
	s_mov_b32 s4, 1
	v_mov_b32_e32 v16, 0
	s_branch .LBB0_313

.Lscan_loop:
	s_and_b32 s7, s6, 3
	s_lshl_b32 s7, s7, 12
	v_add_u32_e32 v23, s7, v22
	ds_read_b128 v[32:35], v10 offset:0
	ds_read_b128 v[48:51], v11 offset:0
	ds_read_b128 v[36:39], v10 offset:64
	ds_read_b128 v[52:55], v12 offset:0
	ds_read_b128 v[40:43], v10 offset:128
	ds_read_b128 v[56:59], v13 offset:0
	ds_read_b128 v[44:47], v10 offset:192
	ds_read_b128 v[60:63], v14 offset:0
	ds_read_u16 v80, v23 offset:0
	ds_read_u16 v81, v23 offset:64
	ds_read_u16 v82, v23 offset:128
	ds_read_u16 v83, v23 offset:192
	s_add_u32 s33, s6, 1
	s_min_u32 s33, s33, 31
	s_add_u32 s36, s6, 2
	s_min_u32 s36, s36, 31
	v_readlane_b32 s37, v24, s6
	s_nop 1
	v_mul_f32_e32 v92, s37, v92
	v_mul_f32_e32 v93, s37, v93
	v_mul_f32_e32 v94, s37, v94
	v_mul_f32_e32 v95, s37, v95
	v_mul_f32_e32 v96, s37, v96
	v_mul_f32_e32 v97, s37, v97
	v_mul_f32_e32 v98, s37, v98
	v_mul_f32_e32 v99, s37, v99
	s_waitcnt lgkmcnt(10)
	v_mfma_f32_16x16x32_bf16 v[84:87], v[48:51], v[32:35], 0
	s_waitcnt lgkmcnt(8)
	v_mfma_f32_16x16x32_bf16 v[84:87], v[52:55], v[36:39], v[84:87]
	s_waitcnt lgkmcnt(6)
	v_mfma_f32_16x16x32_bf16 v[84:87], v[56:59], v[40:43], v[84:87]
	s_waitcnt lgkmcnt(4)
	v_mfma_f32_16x16x32_bf16 v[84:87], v[60:63], v[44:47], v[84:87]
	ds_read_b128 v[64:67], v11 offset:32768
	ds_read_b128 v[68:71], v12 offset:32768
	ds_read_b128 v[72:75], v13 offset:32768
	ds_read_b128 v[76:79], v14 offset:32768
	s_waitcnt lgkmcnt(4)
	v_lshlrev_b32_e32 v80, 16, v80
	v_lshlrev_b32_e32 v81, 16, v81
	v_lshlrev_b32_e32 v82, 16, v82
	v_lshlrev_b32_e32 v83, 16, v83
	v_sub_f32_e32 v26, v80, v84
	v_sub_f32_e32 v27, v81, v85
	v_sub_f32_e32 v28, v82, v86
	v_sub_f32_e32 v29, v83, v87
	v_cvt_pk_bf16_f32 v26, v26, v27
	v_cvt_pk_bf16_f32 v27, v28, v29
	ds_write_b64 v20, v[26:27]
	s_lshl_b32 s7, s33, 14
	s_add_u32 s26, s14, s7
	s_addc_u32 s27, s15, 0
	s_add_i32 m0, s30, 0x14000
	s_nop 0
	global_load_lds_dwordx4 v5, s[26:27]
	s_add_i32 m0, s30, 0x14400
	s_nop 0
	global_load_lds_dwordx4 v6, s[26:27]
	s_lshl_b32 s7, s33, 13
	s_add_u32 s28, s18, s7
	s_addc_u32 s29, s19, 0
	s_add_i32 m0, s31, 0x1a000
	s_nop 0
	global_load_lds_dwordx4 v7, s[28:29]
	s_lshl_b32 s7, s36, 14
	s_add_u32 s26, s24, s7
	s_addc_u32 s27, s25, 0
	s_add_u32 s8, s6, 2
	s_and_b32 s8, s8, 3
	s_lshl_b32 s8, s8, 12
	s_add_u32 s8, s8, s32
	s_add_i32 m0, s8, 0x1f400
	s_nop 0
	global_load_lds_dwordx4 v8, s[26:27]
	s_waitcnt vmcnt(10) lgkmcnt(0)
	s_barrier
	ds_read_b128 v[100:103], v19
	ds_read_b128 v[108:111], v15 offset:0
	ds_read_b128 v[112:115], v15 offset:2048
	ds_read_b128 v[104:107], v19 offset:64
	ds_read_b128 v[116:119], v16 offset:0
	ds_read_b128 v[120:123], v16 offset:2048
	ds_read_b128 v[124:127], v17 offset:0
	ds_read_b128 v[128:131], v18 offset:0
	v_mfma_f32_16x16x32_bf16 v[88:91], v[32:35], v[64:67], 0
	v_mfma_f32_16x16x32_bf16 v[88:91], v[36:39], v[68:71], v[88:91]
	v_mfma_f32_16x16x32_bf16 v[88:91], v[40:43], v[72:75], v[88:91]
	v_mfma_f32_16x16x32_bf16 v[88:91], v[44:47], v[76:79], v[88:91]
	s_waitcnt lgkmcnt(6)
	v_mfma_f32_16x16x32_bf16 v[92:95], v[108:111], v[100:103], v[92:95]
	s_waitcnt lgkmcnt(5)
	v_mfma_f32_16x16x32_bf16 v[96:99], v[112:115], v[100:103], v[96:99]
	s_waitcnt lgkmcnt(3)
	v_mfma_f32_16x16x32_bf16 v[92:95], v[116:119], v[104:107], v[92:95]
	s_waitcnt lgkmcnt(2)
	v_mfma_f32_16x16x32_bf16 v[96:99], v[120:123], v[104:107], v[96:99]
	s_waitcnt lgkmcnt(1)
	v_mfma_f32_16x16x32_bf16 v[88:91], v[100:103], v[124:127], v[88:91]
	s_waitcnt lgkmcnt(0)
	v_mfma_f32_16x16x32_bf16 v[88:91], v[104:107], v[128:131], v[88:91]
	s_lshl_b32 s7, s6, 14
	s_add_u32 s28, s24, s7
	s_addc_u32 s29, s25, 0
	s_nop 1
	v_cvt_pk_bf16_f32 v26, v92, v93
	v_cvt_pk_bf16_f32 v27, v94, v95
	v_cvt_pk_bf16_f32 v28, v96, v97
	v_cvt_pk_bf16_f32 v29, v98, v99
	ds_write_b64 v21, v[26:27]
	ds_write_b64 v21, v[28:29] offset:32
	s_lshl_b32 s7, s36, 14
	s_add_u32 s26, s10, s7
	s_addc_u32 s27, s11, 0
	s_add_i32 m0, s30, 0x0
	s_nop 0
	global_load_lds_dwordx4 v3, s[26:27]
	s_add_i32 m0, s30, 0x400
	s_nop 0
	global_load_lds_dwordx4 v4, s[26:27]
	s_lshl_b32 s7, s36, 14
	s_add_u32 s26, s12, s7
	s_addc_u32 s27, s13, 0
	s_add_i32 m0, s30, 0x8000
	s_nop 0
	global_load_lds_dwordx4 v3, s[26:27]
	s_add_i32 m0, s30, 0x8400
	s_nop 0
	global_load_lds_dwordx4 v4, s[26:27]
	v_cvt_pk_bf16_f32 v80, v88, v89
	v_cvt_pk_bf16_f32 v81, v90, v91
	global_store_dwordx2 v9, v[80:81], s[28:29]
	s_add_u32 s6, s6, 1
	s_waitcnt vmcnt(10) lgkmcnt(0)
	s_barrier
	s_and_b32 s7, s6, 3
	s_lshl_b32 s7, s7, 12
	v_add_u32_e32 v23, s7, v22
	ds_read_b128 v[32:35], v10 offset:0
	ds_read_b128 v[48:51], v11 offset:16384
	ds_read_b128 v[36:39], v10 offset:64
	ds_read_b128 v[52:55], v12 offset:16384
	ds_read_b128 v[40:43], v10 offset:128
	ds_read_b128 v[56:59], v13 offset:16384
	ds_read_b128 v[44:47], v10 offset:192
	ds_read_b128 v[60:63], v14 offset:16384
	ds_read_u16 v80, v23 offset:0
	ds_read_u16 v81, v23 offset:64
	ds_read_u16 v82, v23 offset:128
	ds_read_u16 v83, v23 offset:192
	s_add_u32 s33, s6, 1
	s_min_u32 s33, s33, 31
	s_add_u32 s36, s6, 2
	s_min_u32 s36, s36, 31
	v_readlane_b32 s37, v24, s6
	s_nop 1
	v_mul_f32_e32 v92, s37, v92
	v_mul_f32_e32 v93, s37, v93
	v_mul_f32_e32 v94, s37, v94
	v_mul_f32_e32 v95, s37, v95
	v_mul_f32_e32 v96, s37, v96
	v_mul_f32_e32 v97, s37, v97
	v_mul_f32_e32 v98, s37, v98
	v_mul_f32_e32 v99, s37, v99
	s_waitcnt lgkmcnt(10)
	v_mfma_f32_16x16x32_bf16 v[84:87], v[48:51], v[32:35], 0
	s_waitcnt lgkmcnt(8)
	v_mfma_f32_16x16x32_bf16 v[84:87], v[52:55], v[36:39], v[84:87]
	s_waitcnt lgkmcnt(6)
	v_mfma_f32_16x16x32_bf16 v[84:87], v[56:59], v[40:43], v[84:87]
	s_waitcnt lgkmcnt(4)
	v_mfma_f32_16x16x32_bf16 v[84:87], v[60:63], v[44:47], v[84:87]
	ds_read_b128 v[64:67], v11 offset:49152
	ds_read_b128 v[68:71], v12 offset:49152
	ds_read_b128 v[72:75], v13 offset:49152
	ds_read_b128 v[76:79], v14 offset:49152
	s_waitcnt lgkmcnt(4)
	v_lshlrev_b32_e32 v80, 16, v80
	v_lshlrev_b32_e32 v81, 16, v81
	v_lshlrev_b32_e32 v82, 16, v82
	v_lshlrev_b32_e32 v83, 16, v83
	v_sub_f32_e32 v26, v80, v84
	v_sub_f32_e32 v27, v81, v85
	v_sub_f32_e32 v28, v82, v86
	v_sub_f32_e32 v29, v83, v87
	v_cvt_pk_bf16_f32 v26, v26, v27
	v_cvt_pk_bf16_f32 v27, v28, v29
	ds_write_b64 v20, v[26:27]
	s_lshl_b32 s7, s33, 14
	s_add_u32 s26, s14, s7
	s_addc_u32 s27, s15, 0
	s_add_i32 m0, s30, 0x10000
	s_nop 0
	global_load_lds_dwordx4 v5, s[26:27]
	s_add_i32 m0, s30, 0x10400
	s_nop 0
	global_load_lds_dwordx4 v6, s[26:27]
	s_lshl_b32 s7, s33, 13
	s_add_u32 s28, s18, s7
	s_addc_u32 s29, s19, 0
	s_add_i32 m0, s31, 0x18000
	s_nop 0
	global_load_lds_dwordx4 v7, s[28:29]
	s_lshl_b32 s7, s36, 14
	s_add_u32 s26, s24, s7
	s_addc_u32 s27, s25, 0
	s_add_u32 s8, s6, 2
	s_and_b32 s8, s8, 3
	s_lshl_b32 s8, s8, 12
	s_add_u32 s8, s8, s32
	s_add_i32 m0, s8, 0x1f400
	s_nop 0
	global_load_lds_dwordx4 v8, s[26:27]
	s_waitcnt vmcnt(10) lgkmcnt(0)
	s_barrier
	ds_read_b128 v[100:103], v19
	ds_read_b128 v[108:111], v15 offset:16384
	ds_read_b128 v[112:115], v15 offset:18432
	ds_read_b128 v[104:107], v19 offset:64
	ds_read_b128 v[116:119], v16 offset:16384
	ds_read_b128 v[120:123], v16 offset:18432
	ds_read_b128 v[124:127], v17 offset:8192
	ds_read_b128 v[128:131], v18 offset:8192
	v_mfma_f32_16x16x32_bf16 v[88:91], v[32:35], v[64:67], 0
	v_mfma_f32_16x16x32_bf16 v[88:91], v[36:39], v[68:71], v[88:91]
	v_mfma_f32_16x16x32_bf16 v[88:91], v[40:43], v[72:75], v[88:91]
	v_mfma_f32_16x16x32_bf16 v[88:91], v[44:47], v[76:79], v[88:91]
	s_waitcnt lgkmcnt(6)
	v_mfma_f32_16x16x32_bf16 v[92:95], v[108:111], v[100:103], v[92:95]
	s_waitcnt lgkmcnt(5)
	v_mfma_f32_16x16x32_bf16 v[96:99], v[112:115], v[100:103], v[96:99]
	s_waitcnt lgkmcnt(3)
	v_mfma_f32_16x16x32_bf16 v[92:95], v[116:119], v[104:107], v[92:95]
	s_waitcnt lgkmcnt(2)
	v_mfma_f32_16x16x32_bf16 v[96:99], v[120:123], v[104:107], v[96:99]
	s_waitcnt lgkmcnt(1)
	v_mfma_f32_16x16x32_bf16 v[88:91], v[100:103], v[124:127], v[88:91]
	s_waitcnt lgkmcnt(0)
	v_mfma_f32_16x16x32_bf16 v[88:91], v[104:107], v[128:131], v[88:91]
	s_lshl_b32 s7, s6, 14
	s_add_u32 s28, s24, s7
	s_addc_u32 s29, s25, 0
	s_nop 1
	v_cvt_pk_bf16_f32 v26, v92, v93
	v_cvt_pk_bf16_f32 v27, v94, v95
	v_cvt_pk_bf16_f32 v28, v96, v97
	v_cvt_pk_bf16_f32 v29, v98, v99
	ds_write_b64 v21, v[26:27]
	ds_write_b64 v21, v[28:29] offset:32
	s_lshl_b32 s7, s36, 14
	s_add_u32 s26, s10, s7
	s_addc_u32 s27, s11, 0
	s_add_i32 m0, s30, 0x4000
	s_nop 0
	global_load_lds_dwordx4 v3, s[26:27]
	s_add_i32 m0, s30, 0x4400
	s_nop 0
	global_load_lds_dwordx4 v4, s[26:27]
	s_lshl_b32 s7, s36, 14
	s_add_u32 s26, s12, s7
	s_addc_u32 s27, s13, 0
	s_add_i32 m0, s30, 0xc000
	s_nop 0
	global_load_lds_dwordx4 v3, s[26:27]
	s_add_i32 m0, s30, 0xc400
	s_nop 0
	global_load_lds_dwordx4 v4, s[26:27]
	v_cvt_pk_bf16_f32 v80, v88, v89
	v_cvt_pk_bf16_f32 v81, v90, v91
	global_store_dwordx2 v9, v[80:81], s[28:29]
	s_add_u32 s6, s6, 1
	s_waitcnt vmcnt(10) lgkmcnt(0)
	s_barrier
	s_cmp_lt_u32 s6, 32
	s_cbranch_scc1 .Lscan_loop
	s_lshl_b32 s56, s77, 5
	s_and_b32 s57, s40, 3
	s_lshl_b32 s72, s40, 5
	s_waitcnt vmcnt(0)
	v_readfirstlane_b32 s3, v194
	s_cmp_gt_u32 s3, 63
	s_barrier
	s_cbranch_scc1 .LBB0_421
	s_waitcnt vmcnt(2)
	v_mbcnt_lo_u32_b32 v0, -1, 0
	v_mbcnt_hi_u32_b32 v0, -1, v0
	s_nop 0
	v_cmp_eq_u32_e32 vcc, 0, v0
	s_and_saveexec_b64 s[6:7], vcc
	s_cbranch_execz .LBB0_420
	v_mov_b32_e32 v0, 0x23ff0
	s_waitcnt vmcnt(0) lgkmcnt(0)
	ds_read_b64 v[0:1], v0
	v_mov_b32_e32 v2, 0x23800
	ds_read_b32 v3, v2
	s_getreg_b32 s3, hwreg(HW_REG_XCC_ID, 0, 4)
	s_and_b32 s3, s3, 7
	s_lshl_b32 s3, s3, 8
	s_add_u32 s4, s92, 0x510000
	s_addc_u32 s5, s93, 0
	s_add_u32 s8, s3, 0x36c0
	v_mov_b32_e32 v6, s8
	v_mov_b32_e32 v7, 1
	global_atomic_add v8, v6, v7, s[4:5] sc0
	s_add_u32 s3, s3, 0x3640
	v_mov_b32_e32 v9, s3
	s_waitcnt lgkmcnt(0)
	v_add_u32_e32 v3, 1, v3
	ds_write_b32 v2, v3
	v_mul_lo_u32 v4, v3, v0
	v_mul_lo_u32 v5, v3, v1
	s_waitcnt vmcnt(0)
	v_add_u32_e32 v8, 1, v8
	v_cmp_eq_u32_e32 vcc, v8, v4
	s_cbranch_vccz .Lgb_wait_2
	buffer_wbl2 sc1
	s_waitcnt vmcnt(0)
	v_mov_b32_e32 v10, 0x3e00
	global_atomic_add v11, v10, v7, s[4:5] sc0
	s_waitcnt vmcnt(0)
	v_add_u32_e32 v11, 1, v11
	v_cmp_eq_u32_e32 vcc, v11, v5
	s_cbranch_vccz .Lgb_wait_2
	v_mov_b32_e32 v10, 0x3640
	v_mov_b32_e32 v11, 0x3740
	v_mov_b32_e32 v12, 0x3840
	v_mov_b32_e32 v13, 0x3940
	v_mov_b32_e32 v14, 0x3a40
	v_mov_b32_e32 v15, 0x3b40
	v_mov_b32_e32 v16, 0x3c40
	v_mov_b32_e32 v17, 0x3d40
	global_atomic_add v10, v7, s[4:5]
	global_atomic_add v11, v7, s[4:5]
	global_atomic_add v12, v7, s[4:5]
	global_atomic_add v13, v7, s[4:5]
	global_atomic_add v14, v7, s[4:5]
	global_atomic_add v15, v7, s[4:5]
	global_atomic_add v16, v7, s[4:5]
	global_atomic_add v17, v7, s[4:5]

.LBB0_597:
	s_waitcnt vmcnt(0)
	v_readfirstlane_b32 s0, v194
	v_readlane_b32 s88, v242, 20
	s_cmp_gt_u32 s0, 63
	v_readlane_b32 s89, v242, 21
	s_barrier
	s_cbranch_scc1 .LBB0_651
	v_mbcnt_lo_u32_b32 v0, -1, 0
	v_mbcnt_hi_u32_b32 v0, -1, v0
	s_nop 0
	v_cmp_eq_u32_e32 vcc, 0, v0
	s_and_saveexec_b64 s[0:1], vcc
	s_cbranch_execz .LBB0_650
	v_mov_b32_e32 v0, 0x23ff0
	s_waitcnt vmcnt(0) lgkmcnt(0)
	ds_read_b64 v[0:1], v0
	v_mov_b32_e32 v2, 0x23800
	ds_read_b32 v3, v2
	s_getreg_b32 s3, hwreg(HW_REG_XCC_ID, 0, 4)
	s_and_b32 s3, s3, 7
	s_lshl_b32 s3, s3, 8
	s_add_u32 s4, s92, 0x510000
	s_addc_u32 s5, s93, 0
	s_add_u32 s6, s3, 0x36c0
	v_mov_b32_e32 v6, s6
	v_mov_b32_e32 v7, 1
	global_atomic_add v8, v6, v7, s[4:5] sc0
	s_add_u32 s3, s3, 0x3640
	v_mov_b32_e32 v9, s3
	s_waitcnt lgkmcnt(0)
	v_add_u32_e32 v3, 1, v3
	ds_write_b32 v2, v3
	v_mul_lo_u32 v4, v3, v0
	v_mul_lo_u32 v5, v3, v1
	s_waitcnt vmcnt(0)
	v_add_u32_e32 v8, 1, v8
	v_cmp_eq_u32_e32 vcc, v8, v4
	s_cbranch_vccz .Lgb_wait_3
	buffer_wbl2 sc1
	s_waitcnt vmcnt(0)
	v_mov_b32_e32 v10, 0x3e00
	global_atomic_add v11, v10, v7, s[4:5] sc0
	s_waitcnt vmcnt(0)
	v_add_u32_e32 v11, 1, v11
	v_cmp_eq_u32_e32 vcc, v11, v5
	s_cbranch_vccz .Lgb_wait_3
	v_mov_b32_e32 v10, 0x3640
	v_mov_b32_e32 v11, 0x3740
	v_mov_b32_e32 v12, 0x3840
	v_mov_b32_e32 v13, 0x3940
	v_mov_b32_e32 v14, 0x3a40
	v_mov_b32_e32 v15, 0x3b40
	v_mov_b32_e32 v16, 0x3c40
	v_mov_b32_e32 v17, 0x3d40
	global_atomic_add v10, v7, s[4:5]
	global_atomic_add v11, v7, s[4:5]
	global_atomic_add v12, v7, s[4:5]
	global_atomic_add v13, v7, s[4:5]
	global_atomic_add v14, v7, s[4:5]
	global_atomic_add v15, v7, s[4:5]
	global_atomic_add v16, v7, s[4:5]
	global_atomic_add v17, v7, s[4:5]
.Lgb_wait_3:
	s_mov_b32 s6, 0
.Lgb_spin_3:
	global_load_dword v8, v9, s[4:5] sc1
	s_waitcnt vmcnt(0)
	v_cmp_ge_u32_e32 vcc, v8, v3
	s_cbranch_vccnz .Lgb_done_3
	s_sleep 1
	s_add_u32 s6, s6, 1
	s_cmp_lt_u32 s6, 0x40000
	s_cbranch_scc1 .Lgb_spin_3
